# residual epilogue: second gate-load pair hoisted to fly with the first (one load round trip less per down-GEMM unit)
# baseline (speedup 1.0000x reference)
.LBB0_563:
	s_ashr_i32 s18, s93, 4
	s_mul_hi_i32 s19, s18, 0x12000
	s_mul_i32 s18, s18, 0x12000
	v_lshl_add_u32 v136, s92, 8, v197
	s_add_u32 s18, s74, s18
	s_addc_u32 s19, s85, s19
	v_ashrrev_i32_e32 v137, 31, v136
	v_lshl_add_u64 v[138:139], v[136:137], 2, s[18:19]
	global_load_dwordx4 v[128:131], v[138:139], off offset:16
	global_load_dwordx4 v[132:135], v[138:139], off
	global_load_dwordx4 v[220:223], v[138:139], off offset:528
	global_load_dwordx4 v[224:227], v[138:139], off offset:512
	v_lshlrev_b64 v[182:183], 1, v[136:137]
	v_lshl_add_u64 v[184:185], s[12:13], 0, v[182:183]
	s_mov_b64 s[18:19], 0x80000
	s_and_b64 vcc, exec, s[4:5]
	s_waitcnt vmcnt(2)
	v_pk_mul_f32 v[174:175], v[130:131], 0.5 op_sel_hi:[1,0]
	v_pk_mul_f32 v[176:177], v[134:135], 0.5 op_sel_hi:[1,0]
	v_pk_mul_f32 v[180:181], v[132:133], 0.5 op_sel_hi:[1,0]
	v_pk_mul_f32 v[178:179], v[128:129], 0.5 op_sel_hi:[1,0]
	s_waitcnt vmcnt(1)
	v_pk_mul_f32 v[170:171], v[220:221], 0.5 op_sel_hi:[1,0]
	v_lshl_add_u32 v128, s93, 8, v195
	v_ashrrev_i32_e32 v129, 31, v128
	v_lshlrev_b64 v[186:187], 12, v[128:129]
	v_pk_mul_f32 v[166:167], v[222:223], 0.5 op_sel_hi:[1,0]
	v_lshl_add_u64 v[130:131], v[184:185], 0, v[186:187]
	global_load_dwordx4 v[200:203], v[130:131], off
	global_load_dwordx4 v[152:155], v[130:131], off offset:256
	v_or_b32_e32 v130, 16, v128
	v_ashrrev_i32_e32 v131, 31, v130
	v_lshlrev_b64 v[192:193], 12, v[130:131]
	v_lshl_add_u64 v[130:131], v[184:185], 0, v[192:193]
	global_load_dwordx4 v[148:151], v[130:131], off
	global_load_dwordx4 v[144:147], v[130:131], off offset:256
	v_or_b32_e32 v130, 32, v128
	v_ashrrev_i32_e32 v131, 31, v130
	v_lshlrev_b64 v[190:191], 12, v[130:131]
	v_lshl_add_u64 v[130:131], v[184:185], 0, v[190:191]
	global_load_dwordx4 v[140:143], v[130:131], off
	global_load_dwordx4 v[136:139], v[130:131], off offset:256
	v_or_b32_e32 v128, 48, v128
	v_ashrrev_i32_e32 v129, 31, v128
	v_lshlrev_b64 v[188:189], 12, v[128:129]
	v_lshl_add_u64 v[128:129], v[184:185], 0, v[188:189]
	s_waitcnt vmcnt(6)
	v_pk_mul_f32 v[168:169], v[226:227], 0.5 op_sel_hi:[1,0]
	v_pk_mul_f32 v[172:173], v[224:225], 0.5 op_sel_hi:[1,0]
	global_load_dwordx4 v[132:135], v[128:129], off
	s_nop 0
	global_load_dwordx4 v[128:131], v[128:129], off offset:256
	s_waitcnt vmcnt(7)
	v_cvt_f32_f16_e32 v204, v201
	v_cvt_f32_f16_sdwa v205, v201 dst_sel:DWORD dst_unused:UNUSED_PAD src0_sel:WORD_1
	v_cvt_f32_f16_e32 v206, v200
	v_cvt_f32_f16_sdwa v207, v200 dst_sel:DWORD dst_unused:UNUSED_PAD src0_sel:WORD_1
	v_cvt_f32_f16_e32 v200, v203
	v_cvt_f32_f16_sdwa v201, v203 dst_sel:DWORD dst_unused:UNUSED_PAD src0_sel:WORD_1
	v_cvt_f32_f16_e32 v208, v202
	v_cvt_f32_f16_sdwa v209, v202 dst_sel:DWORD dst_unused:UNUSED_PAD src0_sel:WORD_1
	v_pk_fma_f32 v[124:125], v[124:125], v[180:181], v[206:207]
	v_pk_fma_f32 v[122:123], v[122:123], v[174:175], v[200:201]
	v_pk_fma_f32 v[126:127], v[126:127], v[176:177], v[204:205]
	v_pk_fma_f32 v[120:121], v[120:121], v[178:179], v[208:209]
	v_cvt_pk_f16_f32 v123, v122, v123
	v_cvt_pk_f16_f32 v122, v120, v121
	v_cvt_pk_f16_f32 v120, v124, v125
	v_lshl_add_u64 v[124:125], s[14:15], 0, v[186:187]
	v_cvt_pk_f16_f32 v121, v126, v127
	v_lshl_add_u64 v[124:125], v[124:125], 0, v[182:183]
	global_store_dwordx4 v[124:125], v[120:123], off
	s_waitcnt vmcnt(7)
	v_cvt_f32_f16_e32 v126, v155
	v_cvt_f32_f16_sdwa v127, v155 dst_sel:DWORD dst_unused:UNUSED_PAD src0_sel:WORD_1
	v_cvt_f32_f16_e32 v120, v153
	v_cvt_f32_f16_sdwa v121, v153 dst_sel:DWORD dst_unused:UNUSED_PAD src0_sel:WORD_1
	v_cvt_f32_f16_e32 v122, v152
	v_cvt_f32_f16_sdwa v123, v152 dst_sel:DWORD dst_unused:UNUSED_PAD src0_sel:WORD_1
	v_cvt_f32_f16_e32 v152, v154
	v_cvt_f32_f16_sdwa v153, v154 dst_sel:DWORD dst_unused:UNUSED_PAD src0_sel:WORD_1
	v_pk_fma_f32 v[118:119], v[118:119], v[168:169], v[120:121]
	v_pk_fma_f32 v[116:117], v[116:117], v[172:173], v[122:123]
	v_pk_fma_f32 v[114:115], v[114:115], v[166:167], v[126:127]
	v_pk_fma_f32 v[112:113], v[112:113], v[170:171], v[152:153]
	v_cvt_pk_f16_f32 v115, v114, v115
	v_cvt_pk_f16_f32 v114, v112, v113
	v_cvt_pk_f16_f32 v113, v118, v119
	v_cvt_pk_f16_f32 v112, v116, v117
	global_store_dwordx4 v[124:125], v[112:115], off offset:256
	s_waitcnt vmcnt(7)
	v_cvt_f32_f16_e32 v116, v151
	v_cvt_f32_f16_sdwa v117, v151 dst_sel:DWORD dst_unused:UNUSED_PAD src0_sel:WORD_1
	v_cvt_f32_f16_e32 v114, v148
	v_cvt_f32_f16_sdwa v115, v148 dst_sel:DWORD dst_unused:UNUSED_PAD src0_sel:WORD_1
	v_cvt_f32_f16_e32 v118, v150
	v_cvt_f32_f16_sdwa v119, v150 dst_sel:DWORD dst_unused:UNUSED_PAD src0_sel:WORD_1
	v_cvt_f32_f16_e32 v112, v149
	v_cvt_f32_f16_sdwa v113, v149 dst_sel:DWORD dst_unused:UNUSED_PAD src0_sel:WORD_1
	v_pk_fma_f32 v[108:109], v[108:109], v[180:181], v[114:115]
	v_pk_fma_f32 v[104:105], v[104:105], v[178:179], v[118:119]
	v_pk_fma_f32 v[106:107], v[106:107], v[174:175], v[116:117]
	v_pk_fma_f32 v[110:111], v[110:111], v[176:177], v[112:113]
	v_cvt_pk_f16_f32 v107, v106, v107
	v_cvt_pk_f16_f32 v106, v104, v105
	v_cvt_pk_f16_f32 v104, v108, v109
	v_lshl_add_u64 v[108:109], s[14:15], 0, v[192:193]
	v_cvt_pk_f16_f32 v105, v110, v111
	v_lshl_add_u64 v[108:109], v[108:109], 0, v[182:183]
	global_store_dwordx4 v[108:109], v[104:107], off
	s_waitcnt vmcnt(7)
	v_cvt_f32_f16_e32 v110, v147
	v_cvt_f32_f16_sdwa v111, v147 dst_sel:DWORD dst_unused:UNUSED_PAD src0_sel:WORD_1
	v_cvt_f32_f16_e32 v104, v145
	v_cvt_f32_f16_sdwa v105, v145 dst_sel:DWORD dst_unused:UNUSED_PAD src0_sel:WORD_1
	v_cvt_f32_f16_e32 v106, v144
	v_cvt_f32_f16_sdwa v107, v144 dst_sel:DWORD dst_unused:UNUSED_PAD src0_sel:WORD_1
	v_cvt_f32_f16_e32 v112, v146
	v_cvt_f32_f16_sdwa v113, v146 dst_sel:DWORD dst_unused:UNUSED_PAD src0_sel:WORD_1
	v_pk_fma_f32 v[102:103], v[102:103], v[168:169], v[104:105]
	v_pk_fma_f32 v[100:101], v[100:101], v[172:173], v[106:107]
	v_pk_fma_f32 v[98:99], v[98:99], v[166:167], v[110:111]
	v_pk_fma_f32 v[96:97], v[96:97], v[170:171], v[112:113]
	v_cvt_pk_f16_f32 v99, v98, v99
	v_cvt_pk_f16_f32 v98, v96, v97
	v_cvt_pk_f16_f32 v97, v102, v103
	v_cvt_pk_f16_f32 v96, v100, v101
	global_store_dwordx4 v[108:109], v[96:99], off offset:256
	s_waitcnt vmcnt(7)
	v_cvt_f32_f16_e32 v100, v143
	v_cvt_f32_f16_sdwa v101, v143 dst_sel:DWORD dst_unused:UNUSED_PAD src0_sel:WORD_1
	v_cvt_f32_f16_e32 v98, v140
	v_cvt_f32_f16_sdwa v99, v140 dst_sel:DWORD dst_unused:UNUSED_PAD src0_sel:WORD_1
	v_cvt_f32_f16_e32 v102, v142
	v_cvt_f32_f16_sdwa v103, v142 dst_sel:DWORD dst_unused:UNUSED_PAD src0_sel:WORD_1
	v_cvt_f32_f16_e32 v96, v141
	v_cvt_f32_f16_sdwa v97, v141 dst_sel:DWORD dst_unused:UNUSED_PAD src0_sel:WORD_1
	v_pk_fma_f32 v[92:93], v[92:93], v[180:181], v[98:99]
	v_pk_fma_f32 v[88:89], v[88:89], v[178:179], v[102:103]
	v_pk_fma_f32 v[90:91], v[90:91], v[174:175], v[100:101]
	v_pk_fma_f32 v[94:95], v[94:95], v[176:177], v[96:97]
	v_cvt_pk_f16_f32 v91, v90, v91
	v_cvt_pk_f16_f32 v90, v88, v89
	v_cvt_pk_f16_f32 v88, v92, v93
	v_lshl_add_u64 v[92:93], s[14:15], 0, v[190:191]
	v_cvt_pk_f16_f32 v89, v94, v95
	v_lshl_add_u64 v[92:93], v[92:93], 0, v[182:183]
	global_store_dwordx4 v[92:93], v[88:91], off
	s_waitcnt vmcnt(7)
	v_cvt_f32_f16_e32 v94, v139
	v_cvt_f32_f16_sdwa v95, v139 dst_sel:DWORD dst_unused:UNUSED_PAD src0_sel:WORD_1
	v_cvt_f32_f16_e32 v88, v137
	v_cvt_f32_f16_sdwa v89, v137 dst_sel:DWORD dst_unused:UNUSED_PAD src0_sel:WORD_1
	v_cvt_f32_f16_e32 v90, v136
	v_cvt_f32_f16_sdwa v91, v136 dst_sel:DWORD dst_unused:UNUSED_PAD src0_sel:WORD_1
	v_cvt_f32_f16_e32 v96, v138
	v_cvt_f32_f16_sdwa v97, v138 dst_sel:DWORD dst_unused:UNUSED_PAD src0_sel:WORD_1
	v_pk_fma_f32 v[86:87], v[86:87], v[168:169], v[88:89]
	v_pk_fma_f32 v[84:85], v[84:85], v[172:173], v[90:91]
	v_pk_fma_f32 v[82:83], v[82:83], v[166:167], v[94:95]
	v_pk_fma_f32 v[80:81], v[80:81], v[170:171], v[96:97]
	v_cvt_pk_f16_f32 v83, v82, v83
	v_cvt_pk_f16_f32 v82, v80, v81
	v_cvt_pk_f16_f32 v81, v86, v87
	v_cvt_pk_f16_f32 v80, v84, v85
	global_store_dwordx4 v[92:93], v[80:83], off offset:256
	s_waitcnt vmcnt(7)
	v_cvt_f32_f16_e32 v84, v135
	v_cvt_f32_f16_sdwa v85, v135 dst_sel:DWORD dst_unused:UNUSED_PAD src0_sel:WORD_1
	v_cvt_f32_f16_e32 v82, v132
	v_cvt_f32_f16_sdwa v83, v132 dst_sel:DWORD dst_unused:UNUSED_PAD src0_sel:WORD_1
	v_cvt_f32_f16_e32 v86, v134
	v_cvt_f32_f16_sdwa v87, v134 dst_sel:DWORD dst_unused:UNUSED_PAD src0_sel:WORD_1
	v_cvt_f32_f16_e32 v80, v133
	v_cvt_f32_f16_sdwa v81, v133 dst_sel:DWORD dst_unused:UNUSED_PAD src0_sel:WORD_1
	v_pk_fma_f32 v[76:77], v[76:77], v[180:181], v[82:83]
	v_pk_fma_f32 v[72:73], v[72:73], v[178:179], v[86:87]
	v_pk_fma_f32 v[74:75], v[74:75], v[174:175], v[84:85]
	v_pk_fma_f32 v[78:79], v[78:79], v[176:177], v[80:81]
	v_cvt_pk_f16_f32 v75, v74, v75
	v_cvt_pk_f16_f32 v74, v72, v73
	v_cvt_pk_f16_f32 v72, v76, v77
	v_lshl_add_u64 v[76:77], s[14:15], 0, v[188:189]
	v_cvt_pk_f16_f32 v73, v78, v79
	v_lshl_add_u64 v[76:77], v[76:77], 0, v[182:183]
	global_store_dwordx4 v[76:77], v[72:75], off
	s_waitcnt vmcnt(7)
	v_cvt_f32_f16_e32 v78, v131
	v_cvt_f32_f16_sdwa v79, v131 dst_sel:DWORD dst_unused:UNUSED_PAD src0_sel:WORD_1
	v_cvt_f32_f16_e32 v72, v129
	v_cvt_f32_f16_sdwa v73, v129 dst_sel:DWORD dst_unused:UNUSED_PAD src0_sel:WORD_1
	v_cvt_f32_f16_e32 v74, v128
	v_cvt_f32_f16_sdwa v75, v128 dst_sel:DWORD dst_unused:UNUSED_PAD src0_sel:WORD_1
	v_cvt_f32_f16_e32 v80, v130
	v_cvt_f32_f16_sdwa v81, v130 dst_sel:DWORD dst_unused:UNUSED_PAD src0_sel:WORD_1
	v_pk_fma_f32 v[70:71], v[70:71], v[168:169], v[72:73]
	v_pk_fma_f32 v[68:69], v[68:69], v[172:173], v[74:75]
	v_pk_fma_f32 v[66:67], v[66:67], v[166:167], v[78:79]
	v_pk_fma_f32 v[64:65], v[64:65], v[170:171], v[80:81]
	v_cvt_pk_f16_f32 v67, v66, v67
	v_cvt_pk_f16_f32 v66, v64, v65
	v_cvt_pk_f16_f32 v65, v70, v71
	v_cvt_pk_f16_f32 v64, v68, v69
	global_store_dwordx4 v[76:77], v[64:67], off offset:256
	v_lshl_add_u64 v[98:99], v[186:187], 0, s[18:19]
	v_lshl_add_u64 v[100:101], v[186:187], 0, s[66:67]
	v_lshl_add_u64 v[64:65], v[184:185], 0, v[98:99]
	global_load_dwordx4 v[74:77], v[64:65], off
	global_load_dwordx4 v[78:81], v[64:65], off offset:256
	v_lshl_add_u64 v[64:65], v[184:185], 0, v[100:101]
	global_load_dwordx4 v[82:85], v[64:65], off
	global_load_dwordx4 v[86:89], v[64:65], off offset:256
	v_lshl_add_u64 v[102:103], v[186:187], 0, s[68:69]
	v_lshl_add_u64 v[64:65], v[184:185], 0, v[102:103]
	global_load_dwordx4 v[90:93], v[64:65], off
	global_load_dwordx4 v[94:97], v[64:65], off offset:256
	v_lshl_add_u64 v[72:73], v[186:187], 0, s[70:71]
	v_lshl_add_u64 v[64:65], v[184:185], 0, v[72:73]
	global_load_dwordx4 v[68:71], v[64:65], off
	s_nop 0
	global_load_dwordx4 v[64:67], v[64:65], off offset:256
	s_mov_b64 s[18:19], -1
	s_waitcnt vmcnt(7)
	v_cvt_f32_f16_e32 v104, v75
	v_cvt_f32_f16_sdwa v105, v75 dst_sel:DWORD dst_unused:UNUSED_PAD src0_sel:WORD_1
	v_cvt_f32_f16_e32 v106, v74
	v_cvt_f32_f16_sdwa v107, v74 dst_sel:DWORD dst_unused:UNUSED_PAD src0_sel:WORD_1
	v_cvt_f32_f16_e32 v74, v77
	v_cvt_f32_f16_sdwa v75, v77 dst_sel:DWORD dst_unused:UNUSED_PAD src0_sel:WORD_1
	v_cvt_f32_f16_e32 v108, v76
	v_cvt_f32_f16_sdwa v109, v76 dst_sel:DWORD dst_unused:UNUSED_PAD src0_sel:WORD_1
	v_pk_fma_f32 v[60:61], v[60:61], v[180:181], v[106:107]
	v_pk_fma_f32 v[58:59], v[58:59], v[174:175], v[74:75]
	v_pk_fma_f32 v[62:63], v[62:63], v[176:177], v[104:105]
	v_pk_fma_f32 v[56:57], v[56:57], v[178:179], v[108:109]
	v_cvt_pk_f16_f32 v59, v58, v59
	v_cvt_pk_f16_f32 v58, v56, v57
	v_cvt_pk_f16_f32 v56, v60, v61
	v_lshl_add_u64 v[60:61], s[14:15], 0, v[98:99]
	v_cvt_pk_f16_f32 v57, v62, v63
	v_lshl_add_u64 v[60:61], v[60:61], 0, v[182:183]
	global_store_dwordx4 v[60:61], v[56:59], off
	s_waitcnt vmcnt(7)
	v_cvt_f32_f16_e32 v62, v81
	v_cvt_f32_f16_sdwa v63, v81 dst_sel:DWORD dst_unused:UNUSED_PAD src0_sel:WORD_1
	v_cvt_f32_f16_e32 v56, v79
	v_cvt_f32_f16_sdwa v57, v79 dst_sel:DWORD dst_unused:UNUSED_PAD src0_sel:WORD_1
	v_cvt_f32_f16_e32 v58, v78
	v_cvt_f32_f16_sdwa v59, v78 dst_sel:DWORD dst_unused:UNUSED_PAD src0_sel:WORD_1
	v_cvt_f32_f16_e32 v74, v80
	v_cvt_f32_f16_sdwa v75, v80 dst_sel:DWORD dst_unused:UNUSED_PAD src0_sel:WORD_1
	v_pk_fma_f32 v[54:55], v[54:55], v[168:169], v[56:57]
	v_pk_fma_f32 v[52:53], v[52:53], v[172:173], v[58:59]
	v_pk_fma_f32 v[50:51], v[50:51], v[166:167], v[62:63]
	v_pk_fma_f32 v[48:49], v[48:49], v[170:171], v[74:75]
	v_cvt_pk_f16_f32 v51, v50, v51
	v_cvt_pk_f16_f32 v50, v48, v49
	v_cvt_pk_f16_f32 v49, v54, v55
	v_cvt_pk_f16_f32 v48, v52, v53
	global_store_dwordx4 v[60:61], v[48:51], off offset:256
	s_waitcnt vmcnt(7)
	v_cvt_f32_f16_e32 v52, v85
	v_cvt_f32_f16_sdwa v53, v85 dst_sel:DWORD dst_unused:UNUSED_PAD src0_sel:WORD_1
	v_cvt_f32_f16_e32 v50, v82
	v_cvt_f32_f16_sdwa v51, v82 dst_sel:DWORD dst_unused:UNUSED_PAD src0_sel:WORD_1
	v_cvt_f32_f16_e32 v54, v84
	v_cvt_f32_f16_sdwa v55, v84 dst_sel:DWORD dst_unused:UNUSED_PAD src0_sel:WORD_1
	v_cvt_f32_f16_e32 v48, v83
	v_cvt_f32_f16_sdwa v49, v83 dst_sel:DWORD dst_unused:UNUSED_PAD src0_sel:WORD_1
	v_pk_fma_f32 v[44:45], v[44:45], v[180:181], v[50:51]
	v_pk_fma_f32 v[40:41], v[40:41], v[178:179], v[54:55]
	v_pk_fma_f32 v[42:43], v[42:43], v[174:175], v[52:53]
	v_pk_fma_f32 v[46:47], v[46:47], v[176:177], v[48:49]
	v_cvt_pk_f16_f32 v43, v42, v43
	v_cvt_pk_f16_f32 v42, v40, v41
	v_cvt_pk_f16_f32 v40, v44, v45
	v_lshl_add_u64 v[44:45], s[14:15], 0, v[100:101]
	v_cvt_pk_f16_f32 v41, v46, v47
	v_lshl_add_u64 v[44:45], v[44:45], 0, v[182:183]
	global_store_dwordx4 v[44:45], v[40:43], off
	s_waitcnt vmcnt(7)
	v_cvt_f32_f16_e32 v46, v89
	v_cvt_f32_f16_sdwa v47, v89 dst_sel:DWORD dst_unused:UNUSED_PAD src0_sel:WORD_1
	v_cvt_f32_f16_e32 v40, v87
	v_cvt_f32_f16_sdwa v41, v87 dst_sel:DWORD dst_unused:UNUSED_PAD src0_sel:WORD_1
	v_cvt_f32_f16_e32 v42, v86
	v_cvt_f32_f16_sdwa v43, v86 dst_sel:DWORD dst_unused:UNUSED_PAD src0_sel:WORD_1
	v_cvt_f32_f16_e32 v48, v88
	v_cvt_f32_f16_sdwa v49, v88 dst_sel:DWORD dst_unused:UNUSED_PAD src0_sel:WORD_1
	v_pk_fma_f32 v[38:39], v[38:39], v[168:169], v[40:41]
	v_pk_fma_f32 v[36:37], v[36:37], v[172:173], v[42:43]
	v_pk_fma_f32 v[34:35], v[34:35], v[166:167], v[46:47]
	v_pk_fma_f32 v[32:33], v[32:33], v[170:171], v[48:49]
	v_cvt_pk_f16_f32 v35, v34, v35
	v_cvt_pk_f16_f32 v34, v32, v33
	v_cvt_pk_f16_f32 v33, v38, v39
	v_cvt_pk_f16_f32 v32, v36, v37
	global_store_dwordx4 v[44:45], v[32:35], off offset:256
	s_waitcnt vmcnt(7)
	v_cvt_f32_f16_e32 v36, v93
	v_cvt_f32_f16_sdwa v37, v93 dst_sel:DWORD dst_unused:UNUSED_PAD src0_sel:WORD_1
	v_cvt_f32_f16_e32 v34, v90
	v_cvt_f32_f16_sdwa v35, v90 dst_sel:DWORD dst_unused:UNUSED_PAD src0_sel:WORD_1
	v_cvt_f32_f16_e32 v38, v92
	v_cvt_f32_f16_sdwa v39, v92 dst_sel:DWORD dst_unused:UNUSED_PAD src0_sel:WORD_1
	v_cvt_f32_f16_e32 v32, v91
	v_cvt_f32_f16_sdwa v33, v91 dst_sel:DWORD dst_unused:UNUSED_PAD src0_sel:WORD_1
	v_pk_fma_f32 v[28:29], v[28:29], v[180:181], v[34:35]
	v_pk_fma_f32 v[24:25], v[24:25], v[178:179], v[38:39]
	v_pk_fma_f32 v[26:27], v[26:27], v[174:175], v[36:37]
	v_pk_fma_f32 v[30:31], v[30:31], v[176:177], v[32:33]
	v_cvt_pk_f16_f32 v27, v26, v27
	v_cvt_pk_f16_f32 v26, v24, v25
	v_cvt_pk_f16_f32 v24, v28, v29
	v_lshl_add_u64 v[28:29], s[14:15], 0, v[102:103]
	v_cvt_pk_f16_f32 v25, v30, v31
	v_lshl_add_u64 v[28:29], v[28:29], 0, v[182:183]
	global_store_dwordx4 v[28:29], v[24:27], off
	s_waitcnt vmcnt(7)
	v_cvt_f32_f16_e32 v30, v97
	v_cvt_f32_f16_sdwa v31, v97 dst_sel:DWORD dst_unused:UNUSED_PAD src0_sel:WORD_1
	v_cvt_f32_f16_e32 v24, v95
	v_cvt_f32_f16_sdwa v25, v95 dst_sel:DWORD dst_unused:UNUSED_PAD src0_sel:WORD_1
	v_cvt_f32_f16_e32 v26, v94
	v_cvt_f32_f16_sdwa v27, v94 dst_sel:DWORD dst_unused:UNUSED_PAD src0_sel:WORD_1
	v_cvt_f32_f16_e32 v32, v96
	v_cvt_f32_f16_sdwa v33, v96 dst_sel:DWORD dst_unused:UNUSED_PAD src0_sel:WORD_1
	v_pk_fma_f32 v[22:23], v[22:23], v[168:169], v[24:25]
	v_pk_fma_f32 v[20:21], v[20:21], v[172:173], v[26:27]
	v_pk_fma_f32 v[18:19], v[18:19], v[166:167], v[30:31]
	v_pk_fma_f32 v[16:17], v[16:17], v[170:171], v[32:33]
	v_cvt_pk_f16_f32 v19, v18, v19
	v_cvt_pk_f16_f32 v18, v16, v17
	v_cvt_pk_f16_f32 v17, v22, v23
	v_cvt_pk_f16_f32 v16, v20, v21
	global_store_dwordx4 v[28:29], v[16:19], off offset:256
	s_waitcnt vmcnt(7)
	v_cvt_f32_f16_e32 v20, v71
	v_cvt_f32_f16_sdwa v21, v71 dst_sel:DWORD dst_unused:UNUSED_PAD src0_sel:WORD_1
	v_cvt_f32_f16_e32 v18, v68
	v_cvt_f32_f16_sdwa v19, v68 dst_sel:DWORD dst_unused:UNUSED_PAD src0_sel:WORD_1
	v_cvt_f32_f16_e32 v22, v70
	v_cvt_f32_f16_sdwa v23, v70 dst_sel:DWORD dst_unused:UNUSED_PAD src0_sel:WORD_1
	v_cvt_f32_f16_e32 v16, v69
	v_cvt_f32_f16_sdwa v17, v69 dst_sel:DWORD dst_unused:UNUSED_PAD src0_sel:WORD_1
	v_pk_fma_f32 v[12:13], v[12:13], v[180:181], v[18:19]
	v_pk_fma_f32 v[8:9], v[8:9], v[178:179], v[22:23]
	v_pk_fma_f32 v[10:11], v[10:11], v[174:175], v[20:21]
	v_pk_fma_f32 v[14:15], v[14:15], v[176:177], v[16:17]
	v_cvt_pk_f16_f32 v11, v10, v11
	v_cvt_pk_f16_f32 v10, v8, v9
	v_cvt_pk_f16_f32 v8, v12, v13
	v_lshl_add_u64 v[12:13], s[14:15], 0, v[72:73]
	v_cvt_pk_f16_f32 v9, v14, v15
	v_lshl_add_u64 v[12:13], v[12:13], 0, v[182:183]
	global_store_dwordx4 v[12:13], v[8:11], off
	s_waitcnt vmcnt(7)
	v_cvt_f32_f16_e32 v14, v67
	v_cvt_f32_f16_sdwa v15, v67 dst_sel:DWORD dst_unused:UNUSED_PAD src0_sel:WORD_1
	v_cvt_f32_f16_e32 v8, v65
	v_cvt_f32_f16_sdwa v9, v65 dst_sel:DWORD dst_unused:UNUSED_PAD src0_sel:WORD_1
	v_cvt_f32_f16_e32 v10, v64
	v_cvt_f32_f16_sdwa v11, v64 dst_sel:DWORD dst_unused:UNUSED_PAD src0_sel:WORD_1
	v_cvt_f32_f16_e32 v16, v66
	v_cvt_f32_f16_sdwa v17, v66 dst_sel:DWORD dst_unused:UNUSED_PAD src0_sel:WORD_1
	v_pk_fma_f32 v[6:7], v[6:7], v[168:169], v[8:9]
	v_pk_fma_f32 v[4:5], v[4:5], v[172:173], v[10:11]
	v_pk_fma_f32 v[2:3], v[2:3], v[166:167], v[14:15]
	v_pk_fma_f32 v[0:1], v[0:1], v[170:171], v[16:17]
	v_cvt_pk_f16_f32 v3, v2, v3
	v_cvt_pk_f16_f32 v2, v0, v1
	v_cvt_pk_f16_f32 v1, v6, v7
	v_cvt_pk_f16_f32 v0, v4, v5
	global_store_dwordx4 v[12:13], v[0:3], off offset:256
	s_cbranch_vccnz .LBB0_548
	s_and_b64 vcc, exec, s[2:3]
	s_cbranch_vccnz .LBB0_547
	s_barrier
	s_branch .LBB0_547

.LBB0_2084:
	s_ashr_i32 s18, s92, 4
	s_mul_hi_i32 s19, s18, 0x12000
	s_mul_i32 s18, s18, 0x12000
	v_lshl_add_u32 v136, s91, 8, v196
	s_add_u32 s18, s72, s18
	s_addc_u32 s19, s74, s19
	v_ashrrev_i32_e32 v137, 31, v136
	v_lshl_add_u64 v[138:139], v[136:137], 2, s[18:19]
	global_load_dwordx4 v[128:131], v[138:139], off offset:16
	global_load_dwordx4 v[132:135], v[138:139], off
	global_load_dwordx4 v[220:223], v[138:139], off offset:528
	global_load_dwordx4 v[224:227], v[138:139], off offset:512
	v_lshlrev_b64 v[182:183], 1, v[136:137]
	v_lshl_add_u64 v[184:185], s[12:13], 0, v[182:183]
	s_mov_b64 s[18:19], 0x80000
	s_and_b64 vcc, exec, s[4:5]
	s_waitcnt vmcnt(2)
	v_pk_mul_f32 v[174:175], v[130:131], 0.5 op_sel_hi:[1,0]
	v_pk_mul_f32 v[176:177], v[134:135], 0.5 op_sel_hi:[1,0]
	v_pk_mul_f32 v[180:181], v[132:133], 0.5 op_sel_hi:[1,0]
	v_pk_mul_f32 v[178:179], v[128:129], 0.5 op_sel_hi:[1,0]
	s_waitcnt vmcnt(1)
	v_pk_mul_f32 v[170:171], v[220:221], 0.5 op_sel_hi:[1,0]
	v_lshl_add_u32 v128, s92, 8, v194
	v_ashrrev_i32_e32 v129, 31, v128
	v_lshlrev_b64 v[186:187], 12, v[128:129]
	v_pk_mul_f32 v[166:167], v[222:223], 0.5 op_sel_hi:[1,0]
	v_lshl_add_u64 v[130:131], v[184:185], 0, v[186:187]
	global_load_dwordx4 v[198:201], v[130:131], off
	global_load_dwordx4 v[152:155], v[130:131], off offset:256
	v_or_b32_e32 v130, 16, v128
	v_ashrrev_i32_e32 v131, 31, v130
	v_lshlrev_b64 v[192:193], 12, v[130:131]
	v_lshl_add_u64 v[130:131], v[184:185], 0, v[192:193]
	global_load_dwordx4 v[148:151], v[130:131], off
	global_load_dwordx4 v[144:147], v[130:131], off offset:256
	v_or_b32_e32 v130, 32, v128
	v_ashrrev_i32_e32 v131, 31, v130
	v_lshlrev_b64 v[190:191], 12, v[130:131]
	v_lshl_add_u64 v[130:131], v[184:185], 0, v[190:191]
	global_load_dwordx4 v[140:143], v[130:131], off
	global_load_dwordx4 v[136:139], v[130:131], off offset:256
	v_or_b32_e32 v128, 48, v128
	v_ashrrev_i32_e32 v129, 31, v128
	v_lshlrev_b64 v[188:189], 12, v[128:129]
	v_lshl_add_u64 v[128:129], v[184:185], 0, v[188:189]
	s_waitcnt vmcnt(6)
	v_pk_mul_f32 v[168:169], v[226:227], 0.5 op_sel_hi:[1,0]
	v_pk_mul_f32 v[172:173], v[224:225], 0.5 op_sel_hi:[1,0]
	global_load_dwordx4 v[132:135], v[128:129], off
	s_nop 0
	global_load_dwordx4 v[128:131], v[128:129], off offset:256
	s_waitcnt vmcnt(7)
	v_cvt_f32_f16_e32 v202, v199
	v_cvt_f32_f16_sdwa v203, v199 dst_sel:DWORD dst_unused:UNUSED_PAD src0_sel:WORD_1
	v_cvt_f32_f16_e32 v204, v198
	v_cvt_f32_f16_sdwa v205, v198 dst_sel:DWORD dst_unused:UNUSED_PAD src0_sel:WORD_1
	v_cvt_f32_f16_e32 v198, v201
	v_cvt_f32_f16_sdwa v199, v201 dst_sel:DWORD dst_unused:UNUSED_PAD src0_sel:WORD_1
	v_cvt_f32_f16_e32 v206, v200
	v_cvt_f32_f16_sdwa v207, v200 dst_sel:DWORD dst_unused:UNUSED_PAD src0_sel:WORD_1
	v_pk_fma_f32 v[124:125], v[124:125], v[180:181], v[204:205]
	v_pk_fma_f32 v[122:123], v[122:123], v[174:175], v[198:199]
	v_pk_fma_f32 v[126:127], v[126:127], v[176:177], v[202:203]
	v_pk_fma_f32 v[120:121], v[120:121], v[178:179], v[206:207]
	v_cvt_pk_f16_f32 v123, v122, v123
	v_cvt_pk_f16_f32 v122, v120, v121
	v_cvt_pk_f16_f32 v120, v124, v125
	v_lshl_add_u64 v[124:125], s[14:15], 0, v[186:187]
	v_cvt_pk_f16_f32 v121, v126, v127
	v_lshl_add_u64 v[124:125], v[124:125], 0, v[182:183]
	global_store_dwordx4 v[124:125], v[120:123], off
	s_waitcnt vmcnt(7)
	v_cvt_f32_f16_e32 v126, v155
	v_cvt_f32_f16_sdwa v127, v155 dst_sel:DWORD dst_unused:UNUSED_PAD src0_sel:WORD_1
	v_cvt_f32_f16_e32 v120, v153
	v_cvt_f32_f16_sdwa v121, v153 dst_sel:DWORD dst_unused:UNUSED_PAD src0_sel:WORD_1
	v_cvt_f32_f16_e32 v122, v152
	v_cvt_f32_f16_sdwa v123, v152 dst_sel:DWORD dst_unused:UNUSED_PAD src0_sel:WORD_1
	v_cvt_f32_f16_e32 v152, v154
	v_cvt_f32_f16_sdwa v153, v154 dst_sel:DWORD dst_unused:UNUSED_PAD src0_sel:WORD_1
	v_pk_fma_f32 v[118:119], v[118:119], v[168:169], v[120:121]
	v_pk_fma_f32 v[116:117], v[116:117], v[172:173], v[122:123]
	v_pk_fma_f32 v[114:115], v[114:115], v[166:167], v[126:127]
	v_pk_fma_f32 v[112:113], v[112:113], v[170:171], v[152:153]
	v_cvt_pk_f16_f32 v115, v114, v115
	v_cvt_pk_f16_f32 v114, v112, v113
	v_cvt_pk_f16_f32 v113, v118, v119
	v_cvt_pk_f16_f32 v112, v116, v117
	global_store_dwordx4 v[124:125], v[112:115], off offset:256
	s_waitcnt vmcnt(7)
	v_cvt_f32_f16_e32 v116, v151
	v_cvt_f32_f16_sdwa v117, v151 dst_sel:DWORD dst_unused:UNUSED_PAD src0_sel:WORD_1
	v_cvt_f32_f16_e32 v114, v148
	v_cvt_f32_f16_sdwa v115, v148 dst_sel:DWORD dst_unused:UNUSED_PAD src0_sel:WORD_1
	v_cvt_f32_f16_e32 v118, v150
	v_cvt_f32_f16_sdwa v119, v150 dst_sel:DWORD dst_unused:UNUSED_PAD src0_sel:WORD_1
	v_cvt_f32_f16_e32 v112, v149
	v_cvt_f32_f16_sdwa v113, v149 dst_sel:DWORD dst_unused:UNUSED_PAD src0_sel:WORD_1
	v_pk_fma_f32 v[108:109], v[108:109], v[180:181], v[114:115]
	v_pk_fma_f32 v[104:105], v[104:105], v[178:179], v[118:119]
	v_pk_fma_f32 v[106:107], v[106:107], v[174:175], v[116:117]
	v_pk_fma_f32 v[110:111], v[110:111], v[176:177], v[112:113]
	v_cvt_pk_f16_f32 v107, v106, v107
	v_cvt_pk_f16_f32 v106, v104, v105
	v_cvt_pk_f16_f32 v104, v108, v109
	v_lshl_add_u64 v[108:109], s[14:15], 0, v[192:193]
	v_cvt_pk_f16_f32 v105, v110, v111
	v_lshl_add_u64 v[108:109], v[108:109], 0, v[182:183]
	global_store_dwordx4 v[108:109], v[104:107], off
	s_waitcnt vmcnt(7)
	v_cvt_f32_f16_e32 v110, v147
	v_cvt_f32_f16_sdwa v111, v147 dst_sel:DWORD dst_unused:UNUSED_PAD src0_sel:WORD_1
	v_cvt_f32_f16_e32 v104, v145
	v_cvt_f32_f16_sdwa v105, v145 dst_sel:DWORD dst_unused:UNUSED_PAD src0_sel:WORD_1
	v_cvt_f32_f16_e32 v106, v144
	v_cvt_f32_f16_sdwa v107, v144 dst_sel:DWORD dst_unused:UNUSED_PAD src0_sel:WORD_1
	v_cvt_f32_f16_e32 v112, v146
	v_cvt_f32_f16_sdwa v113, v146 dst_sel:DWORD dst_unused:UNUSED_PAD src0_sel:WORD_1
	v_pk_fma_f32 v[102:103], v[102:103], v[168:169], v[104:105]
	v_pk_fma_f32 v[100:101], v[100:101], v[172:173], v[106:107]
	v_pk_fma_f32 v[98:99], v[98:99], v[166:167], v[110:111]
	v_pk_fma_f32 v[96:97], v[96:97], v[170:171], v[112:113]
	v_cvt_pk_f16_f32 v99, v98, v99
	v_cvt_pk_f16_f32 v98, v96, v97
	v_cvt_pk_f16_f32 v97, v102, v103
	v_cvt_pk_f16_f32 v96, v100, v101
	global_store_dwordx4 v[108:109], v[96:99], off offset:256
	s_waitcnt vmcnt(7)
	v_cvt_f32_f16_e32 v100, v143
	v_cvt_f32_f16_sdwa v101, v143 dst_sel:DWORD dst_unused:UNUSED_PAD src0_sel:WORD_1
	v_cvt_f32_f16_e32 v98, v140
	v_cvt_f32_f16_sdwa v99, v140 dst_sel:DWORD dst_unused:UNUSED_PAD src0_sel:WORD_1
	v_cvt_f32_f16_e32 v102, v142
	v_cvt_f32_f16_sdwa v103, v142 dst_sel:DWORD dst_unused:UNUSED_PAD src0_sel:WORD_1
	v_cvt_f32_f16_e32 v96, v141
	v_cvt_f32_f16_sdwa v97, v141 dst_sel:DWORD dst_unused:UNUSED_PAD src0_sel:WORD_1
	v_pk_fma_f32 v[92:93], v[92:93], v[180:181], v[98:99]
	v_pk_fma_f32 v[88:89], v[88:89], v[178:179], v[102:103]
	v_pk_fma_f32 v[90:91], v[90:91], v[174:175], v[100:101]
	v_pk_fma_f32 v[94:95], v[94:95], v[176:177], v[96:97]
	v_cvt_pk_f16_f32 v91, v90, v91
	v_cvt_pk_f16_f32 v90, v88, v89
	v_cvt_pk_f16_f32 v88, v92, v93
	v_lshl_add_u64 v[92:93], s[14:15], 0, v[190:191]
	v_cvt_pk_f16_f32 v89, v94, v95
	v_lshl_add_u64 v[92:93], v[92:93], 0, v[182:183]
	global_store_dwordx4 v[92:93], v[88:91], off
	s_waitcnt vmcnt(7)
	v_cvt_f32_f16_e32 v94, v139
	v_cvt_f32_f16_sdwa v95, v139 dst_sel:DWORD dst_unused:UNUSED_PAD src0_sel:WORD_1
	v_cvt_f32_f16_e32 v88, v137
	v_cvt_f32_f16_sdwa v89, v137 dst_sel:DWORD dst_unused:UNUSED_PAD src0_sel:WORD_1
	v_cvt_f32_f16_e32 v90, v136
	v_cvt_f32_f16_sdwa v91, v136 dst_sel:DWORD dst_unused:UNUSED_PAD src0_sel:WORD_1
	v_cvt_f32_f16_e32 v96, v138
	v_cvt_f32_f16_sdwa v97, v138 dst_sel:DWORD dst_unused:UNUSED_PAD src0_sel:WORD_1
	v_pk_fma_f32 v[86:87], v[86:87], v[168:169], v[88:89]
	v_pk_fma_f32 v[84:85], v[84:85], v[172:173], v[90:91]
	v_pk_fma_f32 v[82:83], v[82:83], v[166:167], v[94:95]
	v_pk_fma_f32 v[80:81], v[80:81], v[170:171], v[96:97]
	v_cvt_pk_f16_f32 v83, v82, v83
	v_cvt_pk_f16_f32 v82, v80, v81
	v_cvt_pk_f16_f32 v81, v86, v87
	v_cvt_pk_f16_f32 v80, v84, v85
	global_store_dwordx4 v[92:93], v[80:83], off offset:256
	s_waitcnt vmcnt(7)
	v_cvt_f32_f16_e32 v84, v135
	v_cvt_f32_f16_sdwa v85, v135 dst_sel:DWORD dst_unused:UNUSED_PAD src0_sel:WORD_1
	v_cvt_f32_f16_e32 v82, v132
	v_cvt_f32_f16_sdwa v83, v132 dst_sel:DWORD dst_unused:UNUSED_PAD src0_sel:WORD_1
	v_cvt_f32_f16_e32 v86, v134
	v_cvt_f32_f16_sdwa v87, v134 dst_sel:DWORD dst_unused:UNUSED_PAD src0_sel:WORD_1
	v_cvt_f32_f16_e32 v80, v133
	v_cvt_f32_f16_sdwa v81, v133 dst_sel:DWORD dst_unused:UNUSED_PAD src0_sel:WORD_1
	v_pk_fma_f32 v[76:77], v[76:77], v[180:181], v[82:83]
	v_pk_fma_f32 v[72:73], v[72:73], v[178:179], v[86:87]
	v_pk_fma_f32 v[74:75], v[74:75], v[174:175], v[84:85]
	v_pk_fma_f32 v[78:79], v[78:79], v[176:177], v[80:81]
	v_cvt_pk_f16_f32 v75, v74, v75
	v_cvt_pk_f16_f32 v74, v72, v73
	v_cvt_pk_f16_f32 v72, v76, v77
	v_lshl_add_u64 v[76:77], s[14:15], 0, v[188:189]
	v_cvt_pk_f16_f32 v73, v78, v79
	v_lshl_add_u64 v[76:77], v[76:77], 0, v[182:183]
	global_store_dwordx4 v[76:77], v[72:75], off
	s_waitcnt vmcnt(7)
	v_cvt_f32_f16_e32 v78, v131
	v_cvt_f32_f16_sdwa v79, v131 dst_sel:DWORD dst_unused:UNUSED_PAD src0_sel:WORD_1
	v_cvt_f32_f16_e32 v72, v129
	v_cvt_f32_f16_sdwa v73, v129 dst_sel:DWORD dst_unused:UNUSED_PAD src0_sel:WORD_1
	v_cvt_f32_f16_e32 v74, v128
	v_cvt_f32_f16_sdwa v75, v128 dst_sel:DWORD dst_unused:UNUSED_PAD src0_sel:WORD_1
	v_cvt_f32_f16_e32 v80, v130
	v_cvt_f32_f16_sdwa v81, v130 dst_sel:DWORD dst_unused:UNUSED_PAD src0_sel:WORD_1
	v_pk_fma_f32 v[70:71], v[70:71], v[168:169], v[72:73]
	v_pk_fma_f32 v[68:69], v[68:69], v[172:173], v[74:75]
	v_pk_fma_f32 v[66:67], v[66:67], v[166:167], v[78:79]
	v_pk_fma_f32 v[64:65], v[64:65], v[170:171], v[80:81]
	v_cvt_pk_f16_f32 v67, v66, v67
	v_cvt_pk_f16_f32 v66, v64, v65
	v_cvt_pk_f16_f32 v65, v70, v71
	v_cvt_pk_f16_f32 v64, v68, v69
	global_store_dwordx4 v[76:77], v[64:67], off offset:256
	v_lshl_add_u64 v[98:99], v[186:187], 0, s[18:19]
	v_lshl_add_u64 v[100:101], v[186:187], 0, s[66:67]
	v_lshl_add_u64 v[64:65], v[184:185], 0, v[98:99]
	global_load_dwordx4 v[74:77], v[64:65], off
	global_load_dwordx4 v[78:81], v[64:65], off offset:256
	v_lshl_add_u64 v[64:65], v[184:185], 0, v[100:101]
	global_load_dwordx4 v[82:85], v[64:65], off
	global_load_dwordx4 v[86:89], v[64:65], off offset:256
	v_lshl_add_u64 v[102:103], v[186:187], 0, s[68:69]
	v_lshl_add_u64 v[64:65], v[184:185], 0, v[102:103]
	global_load_dwordx4 v[90:93], v[64:65], off
	global_load_dwordx4 v[94:97], v[64:65], off offset:256
	v_lshl_add_u64 v[72:73], v[186:187], 0, s[70:71]
	v_lshl_add_u64 v[64:65], v[184:185], 0, v[72:73]
	global_load_dwordx4 v[68:71], v[64:65], off
	s_nop 0
	global_load_dwordx4 v[64:67], v[64:65], off offset:256
	s_mov_b64 s[18:19], -1
	s_waitcnt vmcnt(7)
	v_cvt_f32_f16_e32 v104, v75
	v_cvt_f32_f16_sdwa v105, v75 dst_sel:DWORD dst_unused:UNUSED_PAD src0_sel:WORD_1
	v_cvt_f32_f16_e32 v106, v74
	v_cvt_f32_f16_sdwa v107, v74 dst_sel:DWORD dst_unused:UNUSED_PAD src0_sel:WORD_1
	v_cvt_f32_f16_e32 v74, v77
	v_cvt_f32_f16_sdwa v75, v77 dst_sel:DWORD dst_unused:UNUSED_PAD src0_sel:WORD_1
	v_cvt_f32_f16_e32 v108, v76
	v_cvt_f32_f16_sdwa v109, v76 dst_sel:DWORD dst_unused:UNUSED_PAD src0_sel:WORD_1
	v_pk_fma_f32 v[60:61], v[60:61], v[180:181], v[106:107]
	v_pk_fma_f32 v[58:59], v[58:59], v[174:175], v[74:75]
	v_pk_fma_f32 v[62:63], v[62:63], v[176:177], v[104:105]
	v_pk_fma_f32 v[56:57], v[56:57], v[178:179], v[108:109]
	v_cvt_pk_f16_f32 v59, v58, v59
	v_cvt_pk_f16_f32 v58, v56, v57
	v_cvt_pk_f16_f32 v56, v60, v61
	v_lshl_add_u64 v[60:61], s[14:15], 0, v[98:99]
	v_cvt_pk_f16_f32 v57, v62, v63
	v_lshl_add_u64 v[60:61], v[60:61], 0, v[182:183]
	global_store_dwordx4 v[60:61], v[56:59], off
	s_waitcnt vmcnt(7)
	v_cvt_f32_f16_e32 v62, v81
	v_cvt_f32_f16_sdwa v63, v81 dst_sel:DWORD dst_unused:UNUSED_PAD src0_sel:WORD_1
	v_cvt_f32_f16_e32 v56, v79
	v_cvt_f32_f16_sdwa v57, v79 dst_sel:DWORD dst_unused:UNUSED_PAD src0_sel:WORD_1
	v_cvt_f32_f16_e32 v58, v78
	v_cvt_f32_f16_sdwa v59, v78 dst_sel:DWORD dst_unused:UNUSED_PAD src0_sel:WORD_1
	v_cvt_f32_f16_e32 v74, v80
	v_cvt_f32_f16_sdwa v75, v80 dst_sel:DWORD dst_unused:UNUSED_PAD src0_sel:WORD_1
	v_pk_fma_f32 v[54:55], v[54:55], v[168:169], v[56:57]
	v_pk_fma_f32 v[52:53], v[52:53], v[172:173], v[58:59]
	v_pk_fma_f32 v[50:51], v[50:51], v[166:167], v[62:63]
	v_pk_fma_f32 v[48:49], v[48:49], v[170:171], v[74:75]
	v_cvt_pk_f16_f32 v51, v50, v51
	v_cvt_pk_f16_f32 v50, v48, v49
	v_cvt_pk_f16_f32 v49, v54, v55
	v_cvt_pk_f16_f32 v48, v52, v53
	global_store_dwordx4 v[60:61], v[48:51], off offset:256
	s_waitcnt vmcnt(7)
	v_cvt_f32_f16_e32 v52, v85
	v_cvt_f32_f16_sdwa v53, v85 dst_sel:DWORD dst_unused:UNUSED_PAD src0_sel:WORD_1
	v_cvt_f32_f16_e32 v50, v82
	v_cvt_f32_f16_sdwa v51, v82 dst_sel:DWORD dst_unused:UNUSED_PAD src0_sel:WORD_1
	v_cvt_f32_f16_e32 v54, v84
	v_cvt_f32_f16_sdwa v55, v84 dst_sel:DWORD dst_unused:UNUSED_PAD src0_sel:WORD_1
	v_cvt_f32_f16_e32 v48, v83
	v_cvt_f32_f16_sdwa v49, v83 dst_sel:DWORD dst_unused:UNUSED_PAD src0_sel:WORD_1
	v_pk_fma_f32 v[44:45], v[44:45], v[180:181], v[50:51]
	v_pk_fma_f32 v[40:41], v[40:41], v[178:179], v[54:55]
	v_pk_fma_f32 v[42:43], v[42:43], v[174:175], v[52:53]
	v_pk_fma_f32 v[46:47], v[46:47], v[176:177], v[48:49]
	v_cvt_pk_f16_f32 v43, v42, v43
	v_cvt_pk_f16_f32 v42, v40, v41
	v_cvt_pk_f16_f32 v40, v44, v45
	v_lshl_add_u64 v[44:45], s[14:15], 0, v[100:101]
	v_cvt_pk_f16_f32 v41, v46, v47
	v_lshl_add_u64 v[44:45], v[44:45], 0, v[182:183]
	global_store_dwordx4 v[44:45], v[40:43], off
	s_waitcnt vmcnt(7)
	v_cvt_f32_f16_e32 v46, v89
	v_cvt_f32_f16_sdwa v47, v89 dst_sel:DWORD dst_unused:UNUSED_PAD src0_sel:WORD_1
	v_cvt_f32_f16_e32 v40, v87
	v_cvt_f32_f16_sdwa v41, v87 dst_sel:DWORD dst_unused:UNUSED_PAD src0_sel:WORD_1
	v_cvt_f32_f16_e32 v42, v86
	v_cvt_f32_f16_sdwa v43, v86 dst_sel:DWORD dst_unused:UNUSED_PAD src0_sel:WORD_1
	v_cvt_f32_f16_e32 v48, v88
	v_cvt_f32_f16_sdwa v49, v88 dst_sel:DWORD dst_unused:UNUSED_PAD src0_sel:WORD_1
	v_pk_fma_f32 v[38:39], v[38:39], v[168:169], v[40:41]
	v_pk_fma_f32 v[36:37], v[36:37], v[172:173], v[42:43]
	v_pk_fma_f32 v[34:35], v[34:35], v[166:167], v[46:47]
	v_pk_fma_f32 v[32:33], v[32:33], v[170:171], v[48:49]
	v_cvt_pk_f16_f32 v35, v34, v35
	v_cvt_pk_f16_f32 v34, v32, v33
	v_cvt_pk_f16_f32 v33, v38, v39
	v_cvt_pk_f16_f32 v32, v36, v37
	global_store_dwordx4 v[44:45], v[32:35], off offset:256
	s_waitcnt vmcnt(7)
	v_cvt_f32_f16_e32 v36, v93
	v_cvt_f32_f16_sdwa v37, v93 dst_sel:DWORD dst_unused:UNUSED_PAD src0_sel:WORD_1
	v_cvt_f32_f16_e32 v34, v90
	v_cvt_f32_f16_sdwa v35, v90 dst_sel:DWORD dst_unused:UNUSED_PAD src0_sel:WORD_1
	v_cvt_f32_f16_e32 v38, v92
	v_cvt_f32_f16_sdwa v39, v92 dst_sel:DWORD dst_unused:UNUSED_PAD src0_sel:WORD_1
	v_cvt_f32_f16_e32 v32, v91
	v_cvt_f32_f16_sdwa v33, v91 dst_sel:DWORD dst_unused:UNUSED_PAD src0_sel:WORD_1
	v_pk_fma_f32 v[28:29], v[28:29], v[180:181], v[34:35]
	v_pk_fma_f32 v[24:25], v[24:25], v[178:179], v[38:39]
	v_pk_fma_f32 v[26:27], v[26:27], v[174:175], v[36:37]
	v_pk_fma_f32 v[30:31], v[30:31], v[176:177], v[32:33]
	v_cvt_pk_f16_f32 v27, v26, v27
	v_cvt_pk_f16_f32 v26, v24, v25
	v_cvt_pk_f16_f32 v24, v28, v29
	v_lshl_add_u64 v[28:29], s[14:15], 0, v[102:103]
	v_cvt_pk_f16_f32 v25, v30, v31
	v_lshl_add_u64 v[28:29], v[28:29], 0, v[182:183]
	global_store_dwordx4 v[28:29], v[24:27], off
	s_waitcnt vmcnt(7)
	v_cvt_f32_f16_e32 v30, v97
	v_cvt_f32_f16_sdwa v31, v97 dst_sel:DWORD dst_unused:UNUSED_PAD src0_sel:WORD_1
	v_cvt_f32_f16_e32 v24, v95
	v_cvt_f32_f16_sdwa v25, v95 dst_sel:DWORD dst_unused:UNUSED_PAD src0_sel:WORD_1
	v_cvt_f32_f16_e32 v26, v94
	v_cvt_f32_f16_sdwa v27, v94 dst_sel:DWORD dst_unused:UNUSED_PAD src0_sel:WORD_1
	v_cvt_f32_f16_e32 v32, v96
	v_cvt_f32_f16_sdwa v33, v96 dst_sel:DWORD dst_unused:UNUSED_PAD src0_sel:WORD_1
	v_pk_fma_f32 v[22:23], v[22:23], v[168:169], v[24:25]
	v_pk_fma_f32 v[20:21], v[20:21], v[172:173], v[26:27]
	v_pk_fma_f32 v[18:19], v[18:19], v[166:167], v[30:31]
	v_pk_fma_f32 v[16:17], v[16:17], v[170:171], v[32:33]
	v_cvt_pk_f16_f32 v19, v18, v19
	v_cvt_pk_f16_f32 v18, v16, v17
	v_cvt_pk_f16_f32 v17, v22, v23
	v_cvt_pk_f16_f32 v16, v20, v21
	global_store_dwordx4 v[28:29], v[16:19], off offset:256
	s_waitcnt vmcnt(7)
	v_cvt_f32_f16_e32 v20, v71
	v_cvt_f32_f16_sdwa v21, v71 dst_sel:DWORD dst_unused:UNUSED_PAD src0_sel:WORD_1
	v_cvt_f32_f16_e32 v18, v68
	v_cvt_f32_f16_sdwa v19, v68 dst_sel:DWORD dst_unused:UNUSED_PAD src0_sel:WORD_1
	v_cvt_f32_f16_e32 v22, v70
	v_cvt_f32_f16_sdwa v23, v70 dst_sel:DWORD dst_unused:UNUSED_PAD src0_sel:WORD_1
	v_cvt_f32_f16_e32 v16, v69
	v_cvt_f32_f16_sdwa v17, v69 dst_sel:DWORD dst_unused:UNUSED_PAD src0_sel:WORD_1
	v_pk_fma_f32 v[12:13], v[12:13], v[180:181], v[18:19]
	v_pk_fma_f32 v[8:9], v[8:9], v[178:179], v[22:23]
	v_pk_fma_f32 v[10:11], v[10:11], v[174:175], v[20:21]
	v_pk_fma_f32 v[14:15], v[14:15], v[176:177], v[16:17]
	v_cvt_pk_f16_f32 v11, v10, v11
	v_cvt_pk_f16_f32 v10, v8, v9
	v_cvt_pk_f16_f32 v8, v12, v13
	v_lshl_add_u64 v[12:13], s[14:15], 0, v[72:73]
	v_cvt_pk_f16_f32 v9, v14, v15
	v_lshl_add_u64 v[12:13], v[12:13], 0, v[182:183]
	global_store_dwordx4 v[12:13], v[8:11], off
	s_waitcnt vmcnt(7)
	v_cvt_f32_f16_e32 v14, v67
	v_cvt_f32_f16_sdwa v15, v67 dst_sel:DWORD dst_unused:UNUSED_PAD src0_sel:WORD_1
	v_cvt_f32_f16_e32 v8, v65
	v_cvt_f32_f16_sdwa v9, v65 dst_sel:DWORD dst_unused:UNUSED_PAD src0_sel:WORD_1
	v_cvt_f32_f16_e32 v10, v64
	v_cvt_f32_f16_sdwa v11, v64 dst_sel:DWORD dst_unused:UNUSED_PAD src0_sel:WORD_1
	v_cvt_f32_f16_e32 v16, v66
	v_cvt_f32_f16_sdwa v17, v66 dst_sel:DWORD dst_unused:UNUSED_PAD src0_sel:WORD_1
	v_pk_fma_f32 v[6:7], v[6:7], v[168:169], v[8:9]
	v_pk_fma_f32 v[4:5], v[4:5], v[172:173], v[10:11]
	v_pk_fma_f32 v[2:3], v[2:3], v[166:167], v[14:15]
	v_pk_fma_f32 v[0:1], v[0:1], v[170:171], v[16:17]
	v_cvt_pk_f16_f32 v3, v2, v3
	v_cvt_pk_f16_f32 v2, v0, v1
	v_cvt_pk_f16_f32 v1, v6, v7
	v_cvt_pk_f16_f32 v0, v4, v5
	global_store_dwordx4 v[12:13], v[0:3], off offset:256
	s_cbranch_vccnz .LBB0_2069
	s_and_b64 vcc, exec, s[2:3]
	s_cbranch_vccnz .LBB0_2068
	s_barrier
	s_branch .LBB0_2068
